# flat-release barrier, early L1 invalidate; XCD leader issues its invalidate together with the L2 write-back
# baseline (speedup 1.0000x reference)
.LBB0_107:
	s_or_b64 exec, exec, s[8:9]
	v_cvt_f32_u32_e32 v4, v2
	s_waitcnt vmcnt(0)
	v_readfirstlane_b32 s3, v3
	v_sub_u32_e32 v3, 0, v2
	v_rcp_iflag_f32_e32 v4, v4
	v_add_u32_e32 v5, s3, v1
	v_mul_f32_e32 v4, 0x4f7ffffe, v4
	v_cvt_u32_f32_e32 v4, v4
	v_mul_lo_u32 v1, v3, v4
	v_mul_hi_u32 v1, v4, v1
	v_add_u32_e32 v1, v4, v1
	v_mul_hi_u32 v1, v5, v1
	v_mul_lo_u32 v3, v1, v2
	v_sub_u32_e32 v3, v5, v3
	v_add_u32_e32 v4, 1, v1
	v_cmp_ge_u32_e32 vcc, v3, v2
	s_nop 1
	v_cndmask_b32_e32 v1, v1, v4, vcc
	v_sub_u32_e32 v4, v3, v2
	v_cndmask_b32_e32 v3, v3, v4, vcc
	v_add_u32_e32 v4, 1, v1
	v_cmp_ge_u32_e32 vcc, v3, v2
	v_add_u32_e32 v3, 1, v5
	s_nop 0
	v_cndmask_b32_e32 v1, v1, v4, vcc
	v_mul_lo_u32 v4, v2, v1
	v_add_u32_e32 v2, v4, v2
	v_cmp_ne_u32_e32 vcc, v3, v2
	s_waitcnt lgkmcnt(0)
	v_add_u32_e32 v4, 1, v1
	v_mul_lo_u32 v4, v4, v0
	s_and_b64 vcc, exec, vcc
	v_mov_b32_e32 v2, 0x3000
	s_cbranch_vccnz .Lxbp_0
	buffer_inv sc1
	buffer_wbl2 sc1
	s_waitcnt vmcnt(0)
	v_mov_b32_e32 v3, 1
	global_atomic_add v2, v3, s[50:51] offset:1024
	s_branch .Lxbq_0

.LBB0_1956:
	s_or_b64 exec, exec, s[6:7]
	v_cvt_f32_u32_e32 v4, v2
	s_waitcnt vmcnt(0)
	v_readfirstlane_b32 s4, v3
	v_sub_u32_e32 v3, 0, v2
	v_rcp_iflag_f32_e32 v4, v4
	v_add_u32_e32 v5, s4, v1
	v_mul_f32_e32 v4, 0x4f7ffffe, v4
	v_cvt_u32_f32_e32 v4, v4
	v_mul_lo_u32 v1, v3, v4
	v_mul_hi_u32 v1, v4, v1
	v_add_u32_e32 v1, v4, v1
	v_mul_hi_u32 v1, v5, v1
	v_mul_lo_u32 v3, v1, v2
	v_sub_u32_e32 v3, v5, v3
	v_add_u32_e32 v4, 1, v1
	v_cmp_ge_u32_e32 vcc, v3, v2
	s_nop 1
	v_cndmask_b32_e32 v1, v1, v4, vcc
	v_sub_u32_e32 v4, v3, v2
	v_cndmask_b32_e32 v3, v3, v4, vcc
	v_add_u32_e32 v4, 1, v1
	v_cmp_ge_u32_e32 vcc, v3, v2
	v_add_u32_e32 v3, 1, v5
	s_nop 0
	v_cndmask_b32_e32 v1, v1, v4, vcc
	v_mul_lo_u32 v4, v2, v1
	v_add_u32_e32 v2, v4, v2
	v_cmp_ne_u32_e32 vcc, v3, v2
	s_waitcnt lgkmcnt(0)
	v_add_u32_e32 v4, 1, v1
	v_mul_lo_u32 v4, v4, v0
	s_and_b64 vcc, exec, vcc
	v_mov_b32_e32 v2, 0x3000
	s_cbranch_vccnz .Lxbp_21
	buffer_inv sc1
	buffer_wbl2 sc1
	s_waitcnt vmcnt(0)
	v_mov_b32_e32 v3, 1
	global_atomic_add v2, v3, s[50:51] offset:1024
	s_branch .Lxbq_21
